# P2b mixture: nt hint on the once-read OB / z streaming loads
# speedup vs baseline: 1.0003x; 1.0003x over previous
.LBB0_531:
	v_ashrrev_i32_e32 v12, 6, v10
	v_add_u32_e32 v10, s14, v10
	v_ashrrev_i32_e32 v13, 31, v12
	v_mad_i64_i32 v[14:15], s[22:23], v12, s15, v[8:9]
	v_cmp_lt_i32_e32 vcc, s20, v10
	v_lshl_add_u64 v[18:19], v[12:13], 0, s[10:11]
	v_lshl_add_u64 v[14:15], v[14:15], 0, v[0:1]
	v_mad_i64_i32 v[28:29], s[22:23], v12, s19, v[6:7]
	v_lshl_add_u64 v[16:17], v[12:13], 4, v[2:3]
	v_lshl_add_u64 v[20:21], v[12:13], 0, s[12:13]
	v_lshlrev_b64 v[12:13], 10, v[12:13]
	s_or_b64 s[2:3], vcc, s[2:3]
	v_lshl_add_u64 v[22:23], v[18:19], 4, v[2:3]
	v_lshlrev_b64 v[18:19], 10, v[18:19]
	v_add_co_u32_e32 v30, vcc, s18, v14
	v_lshl_add_u64 v[24:25], v[20:21], 4, v[2:3]
	v_lshl_add_u64 v[26:27], v[4:5], 0, v[12:13]
	v_lshlrev_b64 v[20:21], 10, v[20:21]
	v_addc_co_u32_e32 v31, vcc, 0, v15, vcc
	global_load_dword v11, v[16:17], off
	global_load_dword v38, v[22:23], off
	global_load_dword v42, v[24:25], off
	global_load_dwordx4 v[12:15], v[26:27], off nt
	v_lshl_add_u64 v[32:33], v[4:5], 0, v[18:19]
	v_lshl_add_u64 v[34:35], v[4:5], 0, v[20:21]
	global_load_dwordx4 v[16:19], v[32:33], off nt
	global_load_dwordx4 v[20:23], v[34:35], off nt
	global_load_dwordx4 v[24:27], v[30:31], off offset:1024 nt
	s_waitcnt vmcnt(4)
	v_max3_f32 v30, v11, v38, v42
	v_sub_f32_e32 v11, v11, v30
	v_sub_f32_e32 v48, v38, v30
	s_waitcnt vmcnt(3)
	v_and_b32_e32 v35, 0xffff0000, v13
	s_waitcnt vmcnt(0)
	v_lshlrev_b32_e32 v32, 16, v24
	v_and_b32_e32 v33, 0xffff0000, v24
	v_lshlrev_b32_e32 v24, 16, v13
	v_lshlrev_b32_e32 v36, 16, v25
	v_and_b32_e32 v37, 0xffff0000, v25
	v_lshlrev_b32_e32 v40, 16, v26
	v_and_b32_e32 v41, 0xffff0000, v26
	v_and_b32_e32 v43, 0xffff0000, v15
	v_lshlrev_b32_e32 v26, 16, v15
	v_lshlrev_b32_e32 v44, 16, v27
	v_and_b32_e32 v45, 0xffff0000, v27
	v_sub_f32_e32 v49, v42, v30
	v_lshlrev_b32_e32 v30, 16, v16
	v_and_b32_e32 v13, 0xffff0000, v16
	v_lshlrev_b32_e32 v46, 16, v20
	v_and_b32_e32 v47, 0xffff0000, v20
	v_lshlrev_b32_e32 v34, 16, v17
	v_and_b32_e32 v25, 0xffff0000, v17
	v_lshlrev_b32_e32 v16, 16, v21
	v_and_b32_e32 v17, 0xffff0000, v21
	v_lshlrev_b32_e32 v38, 16, v18
	v_and_b32_e32 v15, 0xffff0000, v18
	v_lshlrev_b32_e32 v20, 16, v22
	v_and_b32_e32 v21, 0xffff0000, v22
	v_lshlrev_b32_e32 v42, 16, v19
	v_and_b32_e32 v27, 0xffff0000, v19
	v_lshlrev_b32_e32 v18, 16, v23
	v_and_b32_e32 v19, 0xffff0000, v23
	v_exp_f32_e32 v23, v11
	v_exp_f32_e32 v22, v48
	v_exp_f32_e32 v11, v49
	v_and_b32_e32 v31, 0xffff0000, v12
	v_lshlrev_b32_e32 v12, 16, v12
	v_add_f32_e32 v48, v23, v22
	v_add_f32_e32 v48, v11, v48
	v_div_scale_f32 v49, s[22:23], v48, v48, 1.0
	v_rcp_f32_e32 v51, v49
	v_div_scale_f32 v50, vcc, 1.0, v48, 1.0
	v_and_b32_e32 v39, 0xffff0000, v14
	v_fma_f32 v52, -v49, v51, 1.0
	v_fmac_f32_e32 v51, v52, v51
	v_mul_f32_e32 v52, v50, v51
	v_fma_f32 v53, -v49, v52, v50
	v_fmac_f32_e32 v52, v53, v51
	v_fma_f32 v49, -v49, v52, v50
	v_div_fmas_f32 v49, v49, v51, v52
	v_div_fixup_f32 v48, v49, v48, 1.0
	v_lshlrev_b32_e32 v14, 16, v14
	v_pk_mul_f32 v[22:23], v[22:23], v[48:49] op_sel_hi:[1,0]
	v_mul_f32_e32 v50, v11, v48
	v_pk_mul_f32 v[12:13], v[22:23], v[12:13] op_sel:[1,0] op_sel_hi:[0,1]
	v_pk_mul_f32 v[24:25], v[22:23], v[24:25] op_sel:[1,0] op_sel_hi:[0,1]
	v_pk_mul_f32 v[14:15], v[22:23], v[14:15] op_sel:[1,0] op_sel_hi:[0,1]
	v_pk_mul_f32 v[26:27], v[22:23], v[26:27] op_sel:[1,0] op_sel_hi:[0,1]
	v_pk_fma_f32 v[12:13], v[22:23], v[30:31], v[12:13]
	v_pk_fma_f32 v[24:25], v[22:23], v[34:35], v[24:25]
	v_pk_fma_f32 v[14:15], v[22:23], v[38:39], v[14:15]
	v_pk_fma_f32 v[22:23], v[22:23], v[42:43], v[26:27]
	v_pk_fma_f32 v[12:13], v[50:51], v[46:47], v[12:13] op_sel_hi:[0,1,1]
	v_pk_fma_f32 v[16:17], v[50:51], v[16:17], v[24:25] op_sel_hi:[0,1,1]
	v_pk_fma_f32 v[14:15], v[50:51], v[20:21], v[14:15] op_sel_hi:[0,1,1]
	v_pk_fma_f32 v[18:19], v[50:51], v[18:19], v[22:23] op_sel_hi:[0,1,1]
	v_pk_mul_f32 v[12:13], v[12:13], v[32:33]
	v_pk_mul_f32 v[16:17], v[16:17], v[36:37]
	v_pk_mul_f32 v[14:15], v[14:15], v[40:41]
	v_pk_mul_f32 v[18:19], v[18:19], v[44:45]
	v_cvt_pk_bf16_f32 v12, v12, v13
	v_cvt_pk_bf16_f32 v13, v16, v17
	v_cvt_pk_bf16_f32 v14, v14, v15
	v_cvt_pk_bf16_f32 v15, v18, v19
	global_store_dwordx4 v[28:29], v[12:15], off offset:2048
	s_andn2_b64 exec, exec, s[2:3]
	s_cbranch_execnz .LBB0_531
